# accumulator zeroing between GEMM units with v_mov_b64 (half the instructions)
# baseline (speedup 1.0000x reference)
; template <class Epi, class Sched, bool ALIGN_EPI = false, bool SP2 = false, bool HALFM = false>
; __device__ __forceinline__ void gemm_phase(PG8_LAS unsigned char* lds, const Gemm g, const Sched& S, const Epi& E, const int tid_in) {
;     ...
; #pragma unroll
;         for (int a = 0; a < 2; ++a)
; #pragma unroll
;             for (int b = 0; b < 2; ++b)
; #pragma unroll
;                 for (int m = 0; m < 4; ++m)
; #pragma unroll
;                     for (int n = 0; n < 2; ++n) acc[a][b][m][n] = (f32x4){0.f, 0.f, 0.f, 0.f};
;         cur = nxt; cA = nA; cB = nB; ++ui;
.LBB0_70:
	v_lshl_or_b32 v2, s13, 8, v103
	v_lshl_add_u32 v88, s12, 7, v101
	v_ashrrev_i32_e32 v3, 31, v2
	v_or_b32_e32 v84, 16, v88
	v_or_b32_e32 v80, 32, v88
	v_lshlrev_b64 v[76:77], 1, v[2:3]
	v_mad_i64_i32 v[2:3], s[0:1], v84, s97, v[72:73]
	v_or_b32_e32 v74, 48, v88
	v_lshl_add_u64 v[86:87], v[2:3], 0, v[76:77]
	v_mad_i64_i32 v[2:3], s[0:1], v80, s97, v[72:73]
	v_mad_i64_i32 v[4:5], s[0:1], v88, s97, v[72:73]
	v_lshl_add_u64 v[82:83], v[2:3], 0, v[76:77]
	v_mad_i64_i32 v[2:3], s[0:1], v74, s97, v[72:73]
	s_add_u32 s0, s16, 0x60080
	s_addc_u32 s1, s17, 0
	v_lshl_add_u64 v[78:79], v[2:3], 0, v[76:77]
	s_add_u32 s44, s18, 0x100
	v_mov_b32_e32 v2, 0
	v_ashrrev_i32_e32 v89, 31, v88
	v_ashrrev_i32_e32 v85, 31, v84
	v_ashrrev_i32_e32 v81, 31, v80
	v_ashrrev_i32_e32 v75, 31, v74
	v_lshl_add_u64 v[90:91], v[4:5], 0, v[76:77]
	v_lshl_add_u64 v[92:93], s[0:1], 0, v[68:69]
	v_lshl_add_u64 v[94:95], s[0:1], 0, v[70:71]
	s_addc_u32 s45, s19, 0
	s_mov_b32 s46, 0
	s_mov_b64 s[18:19], 0
	v_mov_b32_e32 v3, v2
	v_mov_b64_e32 v[4:5], 0
	v_mov_b64_e32 v[6:7], 0
	v_mov_b64_e32 v[8:9], 0
	v_mov_b64_e32 v[18:19], 0
	v_mov_b64_e32 v[20:21], 0
	v_mov_b64_e32 v[22:23], 0
	v_mov_b64_e32 v[24:25], 0
	v_mov_b64_e32 v[34:35], 0
	v_mov_b64_e32 v[36:37], 0
	v_mov_b64_e32 v[38:39], 0
	v_mov_b64_e32 v[40:41], 0
	v_mov_b64_e32 v[50:51], 0
	v_mov_b64_e32 v[52:53], 0
	v_mov_b64_e32 v[54:55], 0
	v_mov_b64_e32 v[56:57], 0
	v_mov_b64_e32 v[10:11], 0
	v_mov_b64_e32 v[12:13], 0
	v_mov_b64_e32 v[14:15], 0
	v_mov_b64_e32 v[16:17], 0
	v_mov_b64_e32 v[26:27], 0
	v_mov_b64_e32 v[28:29], 0
	v_mov_b64_e32 v[30:31], 0
	v_mov_b64_e32 v[32:33], 0
	v_mov_b64_e32 v[42:43], 0
	v_mov_b64_e32 v[44:45], 0
	v_mov_b64_e32 v[46:47], 0
	v_mov_b64_e32 v[48:49], 0
	v_mov_b64_e32 v[58:59], 0
	v_mov_b64_e32 v[60:61], 0
	v_mov_b64_e32 v[62:63], 0
	v_mov_b64_e32 v[64:65], 0
	s_branch .LBB0_72

; template <class Epi, class Sched, bool ALIGN_EPI = false, bool SP2 = false, bool HALFM = false>
; __device__ __forceinline__ void gemm_phase(PG8_LAS unsigned char* lds, const Gemm g, const Sched& S, const Epi& E, const int tid_in) {
;     ...
; #pragma unroll
;         for (int a = 0; a < 2; ++a)
; #pragma unroll
;             for (int b = 0; b < 2; ++b)
; #pragma unroll
;                 for (int m = 0; m < 4; ++m)
; #pragma unroll
;                     for (int n = 0; n < 2; ++n) acc[a][b][m][n] = (f32x4){0.f, 0.f, 0.f, 0.f};
;         cur = nxt; cA = nA; cB = nB; ++ui;
.LBB0_185:
	s_add_u32 s6, s56, 0x80
	s_addc_u32 s7, s57, 0
	s_add_u32 s31, s8, 0x100
	v_mov_b32_e32 v2, 0
	s_addc_u32 s56, s9, 0
	s_mov_b32 s8, 0
	v_mov_b32_e32 v3, v2
	v_mov_b64_e32 v[4:5], 0
	v_mov_b64_e32 v[6:7], 0
	v_mov_b64_e32 v[8:9], 0
	v_mov_b64_e32 v[18:19], 0
	v_mov_b64_e32 v[20:21], 0
	v_mov_b64_e32 v[22:23], 0
	v_mov_b64_e32 v[24:25], 0
	v_mov_b64_e32 v[34:35], 0
	v_mov_b64_e32 v[36:37], 0
	v_mov_b64_e32 v[38:39], 0
	v_mov_b64_e32 v[40:41], 0
	v_mov_b64_e32 v[50:51], 0
	v_mov_b64_e32 v[52:53], 0
	v_mov_b64_e32 v[54:55], 0
	v_mov_b64_e32 v[56:57], 0
	v_mov_b64_e32 v[10:11], 0
	v_mov_b64_e32 v[12:13], 0
	v_mov_b64_e32 v[14:15], 0
	v_mov_b64_e32 v[16:17], 0
	v_mov_b64_e32 v[26:27], 0
	v_mov_b64_e32 v[28:29], 0
	v_mov_b64_e32 v[30:31], 0
	v_mov_b64_e32 v[32:33], 0
	v_mov_b64_e32 v[42:43], 0
	v_mov_b64_e32 v[44:45], 0
	v_mov_b64_e32 v[46:47], 0
	v_mov_b64_e32 v[48:49], 0
	v_mov_b64_e32 v[58:59], 0
	v_mov_b64_e32 v[60:61], 0
	v_mov_b64_e32 v[62:63], 0
	v_mov_b64_e32 v[64:65], 0
	v_mov_b64_e32 v[66:67], 0
	v_mov_b64_e32 v[68:69], 0
	v_mov_b64_e32 v[70:71], 0
	v_mov_b64_e32 v[72:73], 0
	v_mov_b64_e32 v[82:83], 0
	v_mov_b64_e32 v[84:85], 0
	v_mov_b64_e32 v[86:87], 0
	v_mov_b64_e32 v[88:89], 0
	v_mov_b64_e32 v[98:99], 0
	v_mov_b64_e32 v[100:101], 0
	v_mov_b64_e32 v[102:103], 0
	v_mov_b64_e32 v[104:105], 0
	v_mov_b64_e32 v[114:115], 0
	v_mov_b64_e32 v[116:117], 0
	v_mov_b64_e32 v[118:119], 0
	v_mov_b64_e32 v[120:121], 0
	v_mov_b64_e32 v[74:75], 0
	v_mov_b64_e32 v[76:77], 0
	v_mov_b64_e32 v[78:79], 0
	v_mov_b64_e32 v[80:81], 0
	v_mov_b64_e32 v[90:91], 0
	v_mov_b64_e32 v[92:93], 0
	v_mov_b64_e32 v[94:95], 0
	v_mov_b64_e32 v[96:97], 0
	v_mov_b64_e32 v[106:107], 0
	v_mov_b64_e32 v[108:109], 0
	v_mov_b64_e32 v[110:111], 0
	v_mov_b64_e32 v[112:113], 0
	v_mov_b64_e32 v[122:123], 0
	v_mov_b64_e32 v[124:125], 0
	v_mov_b64_e32 v[126:127], 0
	v_mov_b64_e32 v[128:129], 0

; template <class Epi, class Sched, bool ALIGN_EPI = false, bool SP2 = false, bool HALFM = false>
; __device__ __forceinline__ void gemm_phase(PG8_LAS unsigned char* lds, const Gemm g, const Sched& S, const Epi& E, const int tid_in) {
;     ...
; #pragma unroll
;         for (int a = 0; a < 2; ++a)
; #pragma unroll
;             for (int b = 0; b < 2; ++b)
; #pragma unroll
;                 for (int m = 0; m < 4; ++m)
; #pragma unroll
;                     for (int n = 0; n < 2; ++n) acc[a][b][m][n] = (f32x4){0.f, 0.f, 0.f, 0.f};
;         cur = nxt; cA = nA; cB = nB; ++ui;
.LBB0_243:
	s_add_u32 s6, s10, 0x80
	s_addc_u32 s7, s11, 0
	s_add_u32 s10, s8, 0x100
	v_mov_b32_e32 v2, 0
	s_addc_u32 s11, s9, 0
	s_mov_b32 s8, 0
	v_mov_b32_e32 v3, v2
	v_mov_b64_e32 v[4:5], 0
	v_mov_b64_e32 v[6:7], 0
	v_mov_b64_e32 v[8:9], 0
	v_mov_b64_e32 v[18:19], 0
	v_mov_b64_e32 v[20:21], 0
	v_mov_b64_e32 v[22:23], 0
	v_mov_b64_e32 v[24:25], 0
	v_mov_b64_e32 v[34:35], 0
	v_mov_b64_e32 v[36:37], 0
	v_mov_b64_e32 v[38:39], 0
	v_mov_b64_e32 v[40:41], 0
	v_mov_b64_e32 v[50:51], 0
	v_mov_b64_e32 v[52:53], 0
	v_mov_b64_e32 v[54:55], 0
	v_mov_b64_e32 v[56:57], 0
	v_mov_b64_e32 v[10:11], 0
	v_mov_b64_e32 v[12:13], 0
	v_mov_b64_e32 v[14:15], 0
	v_mov_b64_e32 v[16:17], 0
	v_mov_b64_e32 v[26:27], 0
	v_mov_b64_e32 v[28:29], 0
	v_mov_b64_e32 v[30:31], 0
	v_mov_b64_e32 v[32:33], 0
	v_mov_b64_e32 v[42:43], 0
	v_mov_b64_e32 v[44:45], 0
	v_mov_b64_e32 v[46:47], 0
	v_mov_b64_e32 v[48:49], 0
	v_mov_b64_e32 v[58:59], 0
	v_mov_b64_e32 v[60:61], 0
	v_mov_b64_e32 v[62:63], 0
	v_mov_b64_e32 v[64:65], 0

; template <class Epi, class Sched, bool ALIGN_EPI = false, bool SP2 = false, bool HALFM = false>
; __device__ __forceinline__ void gemm_phase(PG8_LAS unsigned char* lds, const Gemm g, const Sched& S, const Epi& E, const int tid_in) {
;     ...
; #pragma unroll
;         for (int a = 0; a < 2; ++a)
; #pragma unroll
;             for (int b = 0; b < 2; ++b)
; #pragma unroll
;                 for (int m = 0; m < 4; ++m)
; #pragma unroll
;                     for (int n = 0; n < 2; ++n) acc[a][b][m][n] = (f32x4){0.f, 0.f, 0.f, 0.f};
;         cur = nxt; cA = nA; cB = nB; ++ui;
.LBB0_325:
	s_add_u32 s46, s22, 0x100
	v_mov_b32_e32 v2, 0
	s_addc_u32 s47, s23, 0
	s_mov_b32 s48, -2
	v_mov_b32_e32 v3, v2
	v_mov_b64_e32 v[4:5], 0
	v_mov_b64_e32 v[6:7], 0
	v_mov_b64_e32 v[8:9], 0
	v_mov_b64_e32 v[10:11], 0
	v_mov_b64_e32 v[12:13], 0
	v_mov_b64_e32 v[22:23], 0
	v_mov_b64_e32 v[24:25], 0
	v_mov_b64_e32 v[26:27], 0
	v_mov_b64_e32 v[28:29], 0
	v_mov_b64_e32 v[38:39], 0
	v_mov_b64_e32 v[40:41], 0
	v_mov_b64_e32 v[42:43], 0
	v_mov_b64_e32 v[44:45], 0
	v_mov_b64_e32 v[54:55], 0
	v_mov_b64_e32 v[56:57], 0
	v_mov_b64_e32 v[14:15], 0
	v_mov_b64_e32 v[16:17], 0
	v_mov_b64_e32 v[18:19], 0
	v_mov_b64_e32 v[20:21], 0
	v_mov_b64_e32 v[30:31], 0
	v_mov_b64_e32 v[32:33], 0
	v_mov_b64_e32 v[34:35], 0
	v_mov_b64_e32 v[36:37], 0
	v_mov_b64_e32 v[46:47], 0
	v_mov_b64_e32 v[48:49], 0
	v_mov_b64_e32 v[50:51], 0
	v_mov_b64_e32 v[52:53], 0
	v_mov_b64_e32 v[58:59], 0
	v_mov_b64_e32 v[60:61], 0
	v_mov_b64_e32 v[62:63], 0
	v_mov_b64_e32 v[64:65], 0
	v_mov_b64_e32 v[66:67], 0
	v_mov_b64_e32 v[68:69], 0
	v_mov_b64_e32 v[70:71], 0
	v_mov_b64_e32 v[72:73], 0
	v_mov_b64_e32 v[74:75], 0
	v_mov_b64_e32 v[76:77], 0
	v_mov_b64_e32 v[86:87], 0
	v_mov_b64_e32 v[88:89], 0
	v_mov_b64_e32 v[90:91], 0
	v_mov_b64_e32 v[92:93], 0
	v_mov_b64_e32 v[102:103], 0
	v_mov_b64_e32 v[104:105], 0
	v_mov_b64_e32 v[106:107], 0
	v_mov_b64_e32 v[108:109], 0
	v_mov_b64_e32 v[118:119], 0
	v_mov_b64_e32 v[120:121], 0
	v_mov_b64_e32 v[78:79], 0
	v_mov_b64_e32 v[80:81], 0
	v_mov_b64_e32 v[82:83], 0
	v_mov_b64_e32 v[84:85], 0
	v_mov_b64_e32 v[94:95], 0
	v_mov_b64_e32 v[96:97], 0
	v_mov_b64_e32 v[98:99], 0
	v_mov_b64_e32 v[100:101], 0
	v_mov_b64_e32 v[110:111], 0
	v_mov_b64_e32 v[112:113], 0
	v_mov_b64_e32 v[114:115], 0
	v_mov_b64_e32 v[116:117], 0
	v_mov_b64_e32 v[122:123], 0
	v_mov_b64_e32 v[124:125], 0
	v_mov_b64_e32 v[126:127], 0
	v_mov_b64_e32 v[128:129], 0

; template <class Epi, class Sched, bool ALIGN_EPI = false, bool SP2 = false, bool HALFM = false>
; __device__ __forceinline__ void gemm_phase(PG8_LAS unsigned char* lds, const Gemm g, const Sched& S, const Epi& E, const int tid_in) {
;     ...
;         const char* nA = has_next ? (const char*)g.A + (size_t)nxt.pm * astep : cA; const char* nB = has_next ? (const char*)g.Bt + (size_t)nxt.pn * tstep : cB;
;         for (int t = 0; t < nt; t += 2) {
;             if constexpr (Epi::KHOOK) { if (t == 8 || t == 16) E.khook(acc, cur, t, wr, wc, fr, fq); }
;             const bool last = (t == nt - 2);
;             const char* a1 = cA + (size_t)(t + 1) * kstep;
;             const char* a2 = last ? nA : cA + (size_t)(t + 2) * kstep; const char* b2 = last ? nB : cB + (size_t)(t + 2) * kstep;
;     ...
; #pragma unroll
;         for (int a = 0; a < 2; ++a)
; #pragma unroll
;             for (int b = 0; b < 2; ++b)
; #pragma unroll
;                 for (int m = 0; m < 4; ++m)
; #pragma unroll
;                     for (int n = 0; n < 2; ++n) acc[a][b][m][n] = (f32x4){0.f, 0.f, 0.f, 0.f};
;         cur = nxt; cA = nA; cB = nB; ++ui;
.LBB0_351:
	s_ashr_i32 s17, s16, 31
	s_lshl_b64 s[0:1], s[16:17], 18
	s_add_u32 s18, s13, s0
	s_addc_u32 s19, s31, s1
	s_and_b64 s[0:1], s[4:5], exec
	s_cselect_b32 s17, s19, s25
	s_cselect_b32 s44, s18, s24
	s_ashr_i32 s15, s14, 31
	s_lshl_b64 s[0:1], s[14:15], 19
	s_add_u32 s20, s34, s0
	s_addc_u32 s21, s35, s1
	s_and_b64 s[0:1], s[4:5], exec
	s_cselect_b32 s15, s21, s27
	s_cselect_b32 s45, s20, s26
	s_add_u32 s24, s24, 0x40080
	s_addc_u32 s25, s25, 0
	s_add_u32 s46, s26, 0x100
	v_mov_b32_e32 v2, 0
	s_addc_u32 s47, s27, 0
	s_mov_b32 s48, -2
	v_mov_b32_e32 v3, v2
	v_mov_b64_e32 v[4:5], 0
	v_mov_b64_e32 v[6:7], 0
	v_mov_b64_e32 v[8:9], 0
	v_mov_b64_e32 v[18:19], 0
	v_mov_b64_e32 v[20:21], 0
	v_mov_b64_e32 v[22:23], 0
	v_mov_b64_e32 v[24:25], 0
	v_mov_b64_e32 v[34:35], 0
	v_mov_b64_e32 v[36:37], 0
	v_mov_b64_e32 v[38:39], 0
	v_mov_b64_e32 v[40:41], 0
	v_mov_b64_e32 v[50:51], 0
	v_mov_b64_e32 v[52:53], 0
	v_mov_b64_e32 v[54:55], 0
	v_mov_b64_e32 v[56:57], 0
	v_mov_b64_e32 v[10:11], 0
	v_mov_b64_e32 v[12:13], 0
	v_mov_b64_e32 v[14:15], 0
	v_mov_b64_e32 v[16:17], 0
	v_mov_b64_e32 v[26:27], 0
	v_mov_b64_e32 v[28:29], 0
	v_mov_b64_e32 v[30:31], 0
	v_mov_b64_e32 v[32:33], 0
	v_mov_b64_e32 v[42:43], 0
	v_mov_b64_e32 v[44:45], 0
	v_mov_b64_e32 v[46:47], 0
	v_mov_b64_e32 v[48:49], 0
	v_mov_b64_e32 v[58:59], 0
	v_mov_b64_e32 v[60:61], 0
	v_mov_b64_e32 v[62:63], 0
	v_mov_b64_e32 v[64:65], 0

; __device__ __forceinline__ void convert_weights(const KA& A, int L, int sets, LAS float* scr, int gw, int NGW, int lane) {
;     ...
;     if (sets & 4) { u32x4* p = (u32x4*)(ws + W_WIN + (size_t)6336 * 1024 * 2); const int n16 = 64 * 1024 * 2 / 16;
;       unsigned z = 0u; asm volatile("" : "+v"(z)); for (int i = gw * 64 + lane; i < n16; i += NGW * 64) p[i] = (u32x4){z, z, z, z}; }
.LBB0_376:
	v_lshl_add_u32 v6, s2, 6, v130
	s_movk_i32 s0, 0x2000
	v_mov_b32_e32 v2, v1
	v_cmp_gt_i32_e32 vcc, s0, v6
	s_and_saveexec_b64 s[6:7], vcc
	s_cbranch_execz .LBB0_379
	v_ashrrev_i32_e32 v7, 31, v6
	v_lshl_add_u64 v[8:9], v[6:7], 4, s[90:91]
	s_mov_b64 s[0:1], 0x1ee0000
	v_mov_b32_e32 v3, v2
	v_mov_b64_e32 v[4:5], 0
	v_lshl_add_u64 v[8:9], v[8:9], 0, s[0:1]
	s_mov_b64 s[8:9], 0

; template <class Epi, class Sched, bool ALIGN_EPI = false, bool SP2 = false, bool HALFM = false>
; __device__ __forceinline__ void gemm_phase(PG8_LAS unsigned char* lds, const Gemm g, const Sched& S, const Epi& E, const int tid_in) {
;     ...
;         const char* nA = has_next ? (const char*)g.A + (size_t)nxt.pm * astep : cA; const char* nB = has_next ? (const char*)g.Bt + (size_t)nxt.pn * tstep : cB;
;         for (int t = 0; t < nt; t += 2) {
;             if constexpr (Epi::KHOOK) { if (t == 8 || t == 16) E.khook(acc, cur, t, wr, wc, fr, fq); }
;             const bool last = (t == nt - 2);
;             const char* a1 = cA + (size_t)(t + 1) * kstep;
;             const char* a2 = last ? nA : cA + (size_t)(t + 2) * kstep; const char* b2 = last ? nB : cB + (size_t)(t + 2) * kstep;
;     ...
; #pragma unroll
;         for (int a = 0; a < 2; ++a)
; #pragma unroll
;             for (int b = 0; b < 2; ++b)
; #pragma unroll
;                 for (int m = 0; m < 4; ++m)
; #pragma unroll
;                     for (int n = 0; n < 2; ++n) acc[a][b][m][n] = (f32x4){0.f, 0.f, 0.f, 0.f};
;         cur = nxt; cA = nA; cB = nB; ++ui;
.LBB0_394:
	s_ashr_i32 s15, s14, 31
	s_lshl_b64 s[0:1], s[14:15], 19
	s_add_u32 s16, s94, s0
	s_addc_u32 s17, s95, s1
	s_and_b64 s[0:1], s[4:5], exec
	s_cselect_b32 s15, s17, s23
	s_cselect_b32 s42, s16, s22
	s_ashr_i32 s13, s12, 31
	s_lshl_b64 s[0:1], s[12:13], 19
	s_add_u32 s18, s29, s0
	s_addc_u32 s19, s30, s1
	s_and_b64 s[0:1], s[4:5], exec
	s_cselect_b32 s13, s19, s25
	s_cselect_b32 s43, s18, s24
	s_add_u32 s22, s22, 0x40080
	s_addc_u32 s23, s23, 0
	s_add_u32 s44, s24, 0x100
	v_mov_b32_e32 v2, 0
	s_addc_u32 s45, s25, 0
	s_mov_b32 s46, -2
	v_mov_b32_e32 v3, v2
	v_mov_b64_e32 v[4:5], 0
	v_mov_b64_e32 v[10:11], 0
	v_mov_b64_e32 v[12:13], 0
	v_mov_b64_e32 v[18:19], 0
	v_mov_b64_e32 v[20:21], 0
	v_mov_b64_e32 v[26:27], 0
	v_mov_b64_e32 v[28:29], 0
	v_mov_b64_e32 v[34:35], 0
	v_mov_b64_e32 v[36:37], 0
	v_mov_b64_e32 v[42:43], 0
	v_mov_b64_e32 v[44:45], 0
	v_mov_b64_e32 v[50:51], 0
	v_mov_b64_e32 v[52:53], 0
	v_mov_b64_e32 v[58:59], 0
	v_mov_b64_e32 v[60:61], 0
	v_mov_b64_e32 v[6:7], 0
	v_mov_b64_e32 v[8:9], 0
	v_mov_b64_e32 v[14:15], 0
	v_mov_b64_e32 v[16:17], 0
	v_mov_b64_e32 v[22:23], 0
	v_mov_b64_e32 v[24:25], 0
	v_mov_b64_e32 v[30:31], 0
	v_mov_b64_e32 v[32:33], 0
	v_mov_b64_e32 v[38:39], 0
	v_mov_b64_e32 v[40:41], 0
	v_mov_b64_e32 v[46:47], 0
	v_mov_b64_e32 v[48:49], 0
	v_mov_b64_e32 v[54:55], 0
	v_mov_b64_e32 v[56:57], 0
	v_mov_b64_e32 v[62:63], 0
	v_mov_b64_e32 v[64:65], 0
	v_mov_b64_e32 v[66:67], 0
	v_mov_b64_e32 v[68:69], 0
	v_mov_b64_e32 v[74:75], 0
	v_mov_b64_e32 v[76:77], 0
	v_mov_b64_e32 v[82:83], 0
	v_mov_b64_e32 v[84:85], 0
	v_mov_b64_e32 v[90:91], 0
	v_mov_b64_e32 v[92:93], 0
	v_mov_b64_e32 v[98:99], 0
	v_mov_b64_e32 v[100:101], 0
	v_mov_b64_e32 v[106:107], 0
	v_mov_b64_e32 v[108:109], 0
	v_mov_b64_e32 v[114:115], 0
	v_mov_b64_e32 v[116:117], 0
	v_mov_b64_e32 v[122:123], 0
	v_mov_b64_e32 v[124:125], 0
	v_mov_b64_e32 v[70:71], 0
	v_mov_b64_e32 v[72:73], 0
	v_mov_b64_e32 v[78:79], 0
	v_mov_b64_e32 v[80:81], 0
	v_mov_b64_e32 v[86:87], 0
	v_mov_b64_e32 v[88:89], 0
	v_mov_b64_e32 v[94:95], 0
	v_mov_b64_e32 v[96:97], 0
	v_mov_b64_e32 v[102:103], 0
	v_mov_b64_e32 v[104:105], 0
	v_mov_b64_e32 v[110:111], 0
	v_mov_b64_e32 v[112:113], 0
	v_mov_b64_e32 v[118:119], 0
	v_mov_b64_e32 v[120:121], 0
	v_mov_b64_e32 v[126:127], 0
	v_mov_b64_e32 v[128:129], 0

; template <class Epi, class Sched, bool ALIGN_EPI = false, bool SP2 = false, bool HALFM = false>
; __device__ __forceinline__ void gemm_phase(PG8_LAS unsigned char* lds, const Gemm g, const Sched& S, const Epi& E, const int tid_in) {
;     ...
;         const char* nA = has_next ? (const char*)g.A + (size_t)nxt.pm * astep : cA; const char* nB = has_next ? (const char*)g.Bt + (size_t)nxt.pn * tstep : cB;
;         for (int t = 0; t < nt; t += 2) {
;             if constexpr (Epi::KHOOK) { if (t == 8 || t == 16) E.khook(acc, cur, t, wr, wc, fr, fq); }
;             const bool last = (t == nt - 2);
;             const char* a1 = cA + (size_t)(t + 1) * kstep;
;             const char* a2 = last ? nA : cA + (size_t)(t + 2) * kstep; const char* b2 = last ? nB : cB + (size_t)(t + 2) * kstep;
;     ...
; #pragma unroll
;         for (int a = 0; a < 2; ++a)
; #pragma unroll
;             for (int b = 0; b < 2; ++b)
; #pragma unroll
;                 for (int m = 0; m < 4; ++m)
; #pragma unroll
;                     for (int n = 0; n < 2; ++n) acc[a][b][m][n] = (f32x4){0.f, 0.f, 0.f, 0.f};
;         cur = nxt; cA = nA; cB = nB; ++ui;
.LBB0_418:
	s_ashr_i32 s15, s14, 31
	s_lshl_b64 s[0:1], s[14:15], 18
	s_add_u32 s16, s94, s0
	s_addc_u32 s17, s95, s1
	s_and_b64 s[0:1], s[4:5], exec
	s_cselect_b32 s15, s17, s23
	s_cselect_b32 s42, s16, s22
	s_ashr_i32 s13, s12, 31
	s_lshl_b64 s[0:1], s[12:13], 19
	s_add_u32 s18, s29, s0
	s_addc_u32 s19, s30, s1
	s_and_b64 s[0:1], s[4:5], exec
	s_cselect_b32 s13, s19, s25
	s_cselect_b32 s43, s18, s24
	s_add_u32 s22, s22, 0x40080
	s_addc_u32 s23, s23, 0
	s_add_u32 s44, s24, 0x100
	v_mov_b32_e32 v2, 0
	s_addc_u32 s45, s25, 0
	s_mov_b32 s46, -2
	v_mov_b32_e32 v3, v2
	v_mov_b64_e32 v[4:5], 0
	v_mov_b64_e32 v[10:11], 0
	v_mov_b64_e32 v[12:13], 0
	v_mov_b64_e32 v[18:19], 0
	v_mov_b64_e32 v[20:21], 0
	v_mov_b64_e32 v[26:27], 0
	v_mov_b64_e32 v[28:29], 0
	v_mov_b64_e32 v[34:35], 0
	v_mov_b64_e32 v[36:37], 0
	v_mov_b64_e32 v[42:43], 0
	v_mov_b64_e32 v[44:45], 0
	v_mov_b64_e32 v[50:51], 0
	v_mov_b64_e32 v[52:53], 0
	v_mov_b64_e32 v[58:59], 0
	v_mov_b64_e32 v[60:61], 0
	v_mov_b64_e32 v[6:7], 0
	v_mov_b64_e32 v[8:9], 0
	v_mov_b64_e32 v[14:15], 0
	v_mov_b64_e32 v[16:17], 0
	v_mov_b64_e32 v[22:23], 0
	v_mov_b64_e32 v[24:25], 0
	v_mov_b64_e32 v[30:31], 0
	v_mov_b64_e32 v[32:33], 0
	v_mov_b64_e32 v[38:39], 0
	v_mov_b64_e32 v[40:41], 0
	v_mov_b64_e32 v[46:47], 0
	v_mov_b64_e32 v[48:49], 0
	v_mov_b64_e32 v[54:55], 0
	v_mov_b64_e32 v[56:57], 0
	v_mov_b64_e32 v[62:63], 0
	v_mov_b64_e32 v[64:65], 0

; __device__ __forceinline__ void convert_weights(const KA& A, int L, int sets, LAS float* scr, int gw, int NGW, int lane) {
;     ...
;     if (sets & 4) { u32x4* p = (u32x4*)(ws + W_WIN + (size_t)6336 * 1024 * 2); const int n16 = 64 * 1024 * 2 / 16;
;       unsigned z = 0u; asm volatile("" : "+v"(z)); for (int i = gw * 64 + lane; i < n16; i += NGW * 64) p[i] = (u32x4){z, z, z, z}; }
.LBB0_543:
	v_lshl_add_u32 v6, s18, 6, v142
	s_movk_i32 s0, 0x2000
	v_mov_b32_e32 v2, v1
	v_cmp_gt_i32_e32 vcc, s0, v6
	s_and_saveexec_b64 s[2:3], vcc
	s_cbranch_execz .LBB0_546
	v_ashrrev_i32_e32 v7, 31, v6
	v_lshl_add_u64 v[8:9], v[6:7], 4, s[90:91]
	s_mov_b64 s[0:1], 0x1ee0000
	v_mov_b32_e32 v3, v2
	v_mov_b64_e32 v[4:5], 0
	v_lshl_add_u64 v[8:9], v[8:9], 0, s[0:1]
	s_mov_b64 s[4:5], 0
